# in-proj GEMM epilogue stores coalesced too (ds_bpermute lane transpose, per-lane address delta)
# speedup vs baseline: 1.0389x; 1.0135x over previous
; __device__ __forceinline__ unsigned cvt_pk_bf16(float lo, float hi) { unsigned r; asm volatile("v_cvt_pk_bf16_f32 %0, %1, %2" : "=v"(r) : "v"(lo), "v"(hi)); return r; }
;     __device__ __forceinline__ void operator()(const f32x4 (&acc)[2][2][4][2], const Unit& u, int wr, int wc, int fr, int fq) const {
;         const int row0 = u.pm * BM + wr * 64 + fr, col0 = u.pn * BM + wc * 32 + 8 * fq;
; #pragma unroll
;         for (int ai = 0; ai < 2; ++ai)
; #pragma unroll
;             for (int m = 0; m < 4; ++m) {
;                 const int row = row0 + ai * HALF + m * 16;
;                 const f32x4* sp = (const f32x4*)(ss + (size_t)row * 16);
;                 const f32x4 a0 = sp[0], a1 = sp[1], a2 = sp[2], a3 = sp[3];
;                 const float tot = ((a0.x + a0.y) + (a0.z + a0.w)) + ((a1.x + a1.y) + (a1.z + a1.w)) + ((a2.x + a2.y) + (a2.z + a2.w)) + ((a3.x + a3.y) + (a3.z + a3.w));
;                 const float rs = rsqrtf(tot * (1.0f / 1024.0f) + 1e-6f);
;                 bf16_t* rowp = O + (size_t)row * ldc + col0;
; #pragma unroll
;                 for (int bj = 0; bj < 2; ++bj) {
;                     f32x4 v0 = acc[ai][bj][m][0] * rs, v1 = acc[ai][bj][m][1] * rs;
;                     if (ACT == 1) {
; #pragma unroll
;                         for (int e = 0; e < 4; ++e) { float a = fmaxf(v0[e], 0.f); v0[e] = a * a; float b = fmaxf(v1[e], 0.f); v1[e] = b * b; }
;                     }
;                     u32x4 w; w.x = cvt_pk_bf16(v0[0], v0[1]); w.y = cvt_pk_bf16(v0[2], v0[3]); w.z = cvt_pk_bf16(v1[0], v1[1]); w.w = cvt_pk_bf16(v1[2], v1[3]);
;                     *(u32x4*)(rowp + bj * HALF) = w;
.LBB0_429:
	v_lshl_add_u32 v154, s24, 8, v156
	v_ashrrev_i32_e32 v155, 31, v154
	v_lshlrev_b64 v[160:161], 6, v[154:155]
	v_lshl_add_u64 v[172:173], s[90:91], 0, v[160:161]
	global_load_dwordx4 v[160:163], v[172:173], off offset:48
	global_load_dwordx4 v[164:167], v[172:173], off offset:32
	global_load_dwordx4 v[168:171], v[172:173], off offset:16
	s_nop 0
	global_load_dwordx4 v[172:175], v[172:173], off
	v_lshl_or_b32 v152, s25, 8, v158
	v_ashrrev_i32_e32 v153, 31, v152
	v_lshlrev_b64 v[152:153], 1, v[152:153]
	v_bfe_u32 v228, v204, 2, 4
	v_and_b32_e32 v229, 15, v204
	v_sub_u32_e32 v229, v228, v229
	v_mul_i32_i24_e32 v229, s49, v229
	v_and_b32_e32 v231, 3, v204
	v_bfe_u32 v232, v204, 4, 2
	v_sub_u32_e32 v232, v231, v232
	v_lshl_add_u32 v229, v232, 3, v229
	v_lshlrev_b32_e32 v232, 1, v229
	v_ashrrev_i32_e32 v233, 31, v232
	v_lshl_add_u64 v[152:153], v[152:153], 0, v[232:233]
	v_lshl_add_u32 v230, v231, 4, v228
	v_lshlrev_b32_e32 v230, 2, v230
	v_readlane_b32 s76, v250, 21
	v_readlane_b32 s92, v250, 23
	v_readlane_b32 s96, v250, 25
	v_readlane_b32 s77, v250, 22
	v_readlane_b32 s93, v250, 24
	v_readlane_b32 s97, v250, 26
	s_waitcnt vmcnt(0)
	v_add_f32_e32 v164, v164, v165
	v_add_f32_e32 v166, v166, v167
	v_mov_b32_e32 v176, v173
	v_mov_b32_e32 v177, v174
	v_mov_b32_e32 v173, v175
	v_mov_b32_e32 v174, v169
	v_mov_b32_e32 v175, v170
	v_mov_b32_e32 v169, v171
	v_pk_add_f32 v[172:173], v[176:177], v[172:173]
	v_pk_add_f32 v[168:169], v[174:175], v[168:169]
	v_pk_add_f32 v[172:173], v[172:173], v[172:173] op_sel:[0,1] op_sel_hi:[1,0]
	v_pk_add_f32 v[168:169], v[168:169], v[168:169] op_sel:[0,1] op_sel_hi:[1,0]
	v_mov_b32_e32 v173, v160
	v_mov_b32_e32 v169, v161
	v_mov_b32_e32 v165, v162
	v_mov_b32_e32 v167, v163
	v_pk_add_f32 v[160:161], v[172:173], v[168:169]
	v_pk_add_f32 v[162:163], v[164:165], v[166:167]
	s_nop 0
	v_pk_add_f32 v[160:161], v[160:161], v[162:163]
	v_mad_i64_i32 v[162:163], s[24:25], v154, s49, 0
	v_add_f32_e32 v155, v160, v161
	v_fmamk_f32 v155, v155, 0x3a800000, v137
	v_cmp_gt_f32_e32 vcc, s4, v155
	v_mul_f32_e32 v160, 0x4b800000, v155
	v_lshl_add_u64 v[162:163], v[162:163], 1, s[78:79]
	v_cndmask_b32_e32 v155, v155, v160, vcc
	v_rsq_f32_e32 v155, v155
	v_lshl_add_u64 v[162:163], v[162:163], 0, v[152:153]
	v_mul_f32_e32 v160, 0x45800000, v155
	v_cndmask_b32_e32 v160, v155, v160, vcc
	v_pk_mul_f32 v[126:127], v[126:127], v[160:161] op_sel_hi:[1,0]
	v_pk_mul_f32 v[124:125], v[124:125], v[160:161] op_sel_hi:[1,0]
	v_pk_mul_f32 v[164:165], v[122:123], v[160:161] op_sel_hi:[1,0]
	v_pk_mul_f32 v[122:123], v[120:121], v[160:161] op_sel_hi:[1,0]
	v_cvt_pk_bf16_f32 v120, v124, v125
	v_cvt_pk_bf16_f32 v121, v126, v127
	v_pk_mul_f32 v[118:119], v[118:119], v[160:161] op_sel_hi:[1,0]
	v_cvt_pk_bf16_f32 v122, v122, v123
	v_cvt_pk_bf16_f32 v123, v164, v165
	ds_bpermute_b32 v208, v230, v120
	ds_bpermute_b32 v209, v230, v121
	ds_bpermute_b32 v210, v230, v122
	ds_bpermute_b32 v211, v230, v123
	v_pk_mul_f32 v[116:117], v[116:117], v[160:161] op_sel_hi:[1,0]
	s_nop 0
	v_pk_mul_f32 v[120:121], v[114:115], v[160:161] op_sel_hi:[1,0]
	v_pk_mul_f32 v[114:115], v[112:113], v[160:161] op_sel_hi:[1,0]
	v_or_b32_e32 v160, 16, v154
	v_cvt_pk_bf16_f32 v112, v116, v117
	v_cvt_pk_bf16_f32 v113, v118, v119
	v_ashrrev_i32_e32 v161, 31, v160
	v_cvt_pk_bf16_f32 v114, v114, v115
	v_cvt_pk_bf16_f32 v115, v120, v121
	ds_bpermute_b32 v212, v230, v112
	ds_bpermute_b32 v213, v230, v113
	ds_bpermute_b32 v214, v230, v114
	ds_bpermute_b32 v215, v230, v115
	s_waitcnt lgkmcnt(4)
	global_store_dwordx4 v[162:163], v[208:211], off
	s_waitcnt lgkmcnt(0)
	global_store_dwordx4 v[162:163], v[212:215], off offset:256
	s_nop 1
	v_lshlrev_b64 v[112:113], 6, v[160:161]
	v_lshl_add_u64 v[124:125], s[90:91], 0, v[112:113]
	global_load_dwordx4 v[112:115], v[124:125], off offset:48
	global_load_dwordx4 v[116:119], v[124:125], off offset:32
	global_load_dwordx4 v[120:123], v[124:125], off offset:16
	s_nop 0
	global_load_dwordx4 v[124:127], v[124:125], off
	s_waitcnt vmcnt(2)
	v_add_f32_e32 v116, v116, v117
	v_add_f32_e32 v118, v118, v119
	s_waitcnt vmcnt(0)
	v_mov_b32_e32 v162, v125
	v_mov_b32_e32 v163, v126
	v_mov_b32_e32 v125, v127
	v_mov_b32_e32 v126, v121
	v_mov_b32_e32 v127, v122
	v_mov_b32_e32 v121, v123
	v_pk_add_f32 v[124:125], v[162:163], v[124:125]
	v_pk_add_f32 v[120:121], v[126:127], v[120:121]
	v_pk_add_f32 v[124:125], v[124:125], v[124:125] op_sel:[0,1] op_sel_hi:[1,0]
	v_pk_add_f32 v[120:121], v[120:121], v[120:121] op_sel:[0,1] op_sel_hi:[1,0]
	v_mov_b32_e32 v125, v112
	v_mov_b32_e32 v121, v113
	v_mov_b32_e32 v117, v114
	v_mov_b32_e32 v119, v115
	v_pk_add_f32 v[112:113], v[124:125], v[120:121]
	v_pk_add_f32 v[114:115], v[116:117], v[118:119]
	s_nop 0
	v_pk_add_f32 v[112:113], v[112:113], v[114:115]
	v_mad_i64_i32 v[114:115], s[24:25], v160, s49, 0
	v_add_f32_e32 v112, v112, v113
	v_fmamk_f32 v112, v112, 0x3a800000, v137
	v_cmp_gt_f32_e32 vcc, s4, v112
	v_mul_f32_e32 v113, 0x4b800000, v112
	v_lshl_add_u64 v[114:115], v[114:115], 1, s[78:79]
	v_cndmask_b32_e32 v112, v112, v113, vcc
	v_rsq_f32_e32 v112, v112
	v_lshl_add_u64 v[114:115], v[114:115], 0, v[152:153]
	v_mul_f32_e32 v113, 0x45800000, v112
	v_cndmask_b32_e32 v112, v112, v113, vcc
	v_pk_mul_f32 v[110:111], v[110:111], v[112:113] op_sel_hi:[1,0]
	v_pk_mul_f32 v[108:109], v[108:109], v[112:113] op_sel_hi:[1,0]
	v_pk_mul_f32 v[116:117], v[106:107], v[112:113] op_sel_hi:[1,0]
	v_pk_mul_f32 v[106:107], v[104:105], v[112:113] op_sel_hi:[1,0]
	v_cvt_pk_bf16_f32 v104, v108, v109
	v_cvt_pk_bf16_f32 v105, v110, v111
	v_pk_mul_f32 v[102:103], v[102:103], v[112:113] op_sel_hi:[1,0]
	v_cvt_pk_bf16_f32 v106, v106, v107
	v_cvt_pk_bf16_f32 v107, v116, v117
	ds_bpermute_b32 v208, v230, v104
	ds_bpermute_b32 v209, v230, v105
	ds_bpermute_b32 v210, v230, v106
	ds_bpermute_b32 v211, v230, v107
	v_pk_mul_f32 v[100:101], v[100:101], v[112:113] op_sel_hi:[1,0]
	s_nop 0
	v_pk_mul_f32 v[104:105], v[98:99], v[112:113] op_sel_hi:[1,0]
	v_pk_mul_f32 v[98:99], v[96:97], v[112:113] op_sel_hi:[1,0]
	v_or_b32_e32 v112, 32, v154
	v_cvt_pk_bf16_f32 v96, v100, v101
	v_cvt_pk_bf16_f32 v97, v102, v103
	v_ashrrev_i32_e32 v113, 31, v112
	v_cvt_pk_bf16_f32 v98, v98, v99
	v_cvt_pk_bf16_f32 v99, v104, v105
	ds_bpermute_b32 v212, v230, v96
	ds_bpermute_b32 v213, v230, v97
	ds_bpermute_b32 v214, v230, v98
	ds_bpermute_b32 v215, v230, v99
	s_waitcnt lgkmcnt(4)
; __device__ __forceinline__ unsigned cvt_pk_bf16(float lo, float hi) { unsigned r; asm volatile("v_cvt_pk_bf16_f32 %0, %1, %2" : "=v"(r) : "v"(lo), "v"(hi)); return r; }
;     __device__ __forceinline__ void operator()(const f32x4 (&acc)[2][2][4][2], const Unit& u, int wr, int wc, int fr, int fq) const {
;     ...
;                 const int row = row0 + ai * HALF + m * 16;
;                 const f32x4* sp = (const f32x4*)(ss + (size_t)row * 16);
;                 const f32x4 a0 = sp[0], a1 = sp[1], a2 = sp[2], a3 = sp[3];
;                 const float tot = ((a0.x + a0.y) + (a0.z + a0.w)) + ((a1.x + a1.y) + (a1.z + a1.w)) + ((a2.x + a2.y) + (a2.z + a2.w)) + ((a3.x + a3.y) + (a3.z + a3.w));
;                 const float rs = rsqrtf(tot * (1.0f / 1024.0f) + 1e-6f);
;                 bf16_t* rowp = O + (size_t)row * ldc + col0;
; #pragma unroll
;                 for (int bj = 0; bj < 2; ++bj) {
;                     f32x4 v0 = acc[ai][bj][m][0] * rs, v1 = acc[ai][bj][m][1] * rs;
;                     if (ACT == 1) {
; #pragma unroll
;                         for (int e = 0; e < 4; ++e) { float a = fmaxf(v0[e], 0.f); v0[e] = a * a; float b = fmaxf(v1[e], 0.f); v1[e] = b * b; }
;                     }
;                     u32x4 w; w.x = cvt_pk_bf16(v0[0], v0[1]); w.y = cvt_pk_bf16(v0[2], v0[3]); w.z = cvt_pk_bf16(v1[0], v1[1]); w.w = cvt_pk_bf16(v1[2], v1[3]);
;                     *(u32x4*)(rowp + bj * HALF) = w;
	global_store_dwordx4 v[114:115], v[208:211], off
	s_waitcnt lgkmcnt(0)
	global_store_dwordx4 v[114:115], v[212:215], off offset:256
	s_nop 1
	v_lshlrev_b64 v[96:97], 6, v[112:113]
	v_lshl_add_u64 v[108:109], s[90:91], 0, v[96:97]
	global_load_dwordx4 v[96:99], v[108:109], off offset:48
	global_load_dwordx4 v[100:103], v[108:109], off offset:32
	global_load_dwordx4 v[104:107], v[108:109], off offset:16
	s_nop 0
	global_load_dwordx4 v[108:111], v[108:109], off
	s_waitcnt vmcnt(2)
	v_add_f32_e32 v100, v100, v101
	v_add_f32_e32 v102, v102, v103
	s_waitcnt vmcnt(0)
	v_mov_b32_e32 v114, v109
	v_mov_b32_e32 v115, v110
	v_mov_b32_e32 v109, v111
	v_mov_b32_e32 v110, v105
	v_mov_b32_e32 v111, v106
	v_mov_b32_e32 v105, v107
	v_pk_add_f32 v[108:109], v[114:115], v[108:109]
	v_pk_add_f32 v[104:105], v[110:111], v[104:105]
	v_pk_add_f32 v[108:109], v[108:109], v[108:109] op_sel:[0,1] op_sel_hi:[1,0]
	v_pk_add_f32 v[104:105], v[104:105], v[104:105] op_sel:[0,1] op_sel_hi:[1,0]
	v_mov_b32_e32 v109, v96
	v_mov_b32_e32 v105, v97
	v_mov_b32_e32 v101, v98
	v_mov_b32_e32 v103, v99
	v_pk_add_f32 v[96:97], v[108:109], v[104:105]
	v_pk_add_f32 v[98:99], v[100:101], v[102:103]
	s_nop 0
	v_pk_add_f32 v[96:97], v[96:97], v[98:99]
	v_mad_i64_i32 v[98:99], s[24:25], v112, s49, 0
	v_add_f32_e32 v96, v96, v97
	v_fmamk_f32 v96, v96, 0x3a800000, v137
	v_cmp_gt_f32_e32 vcc, s4, v96
	v_mul_f32_e32 v97, 0x4b800000, v96
	v_lshl_add_u64 v[98:99], v[98:99], 1, s[78:79]
	v_cndmask_b32_e32 v96, v96, v97, vcc
	v_rsq_f32_e32 v96, v96
	v_lshl_add_u64 v[98:99], v[98:99], 0, v[152:153]
	v_mul_f32_e32 v97, 0x45800000, v96
	v_cndmask_b32_e32 v96, v96, v97, vcc
	v_pk_mul_f32 v[94:95], v[94:95], v[96:97] op_sel_hi:[1,0]
	v_pk_mul_f32 v[92:93], v[92:93], v[96:97] op_sel_hi:[1,0]
	v_pk_mul_f32 v[100:101], v[90:91], v[96:97] op_sel_hi:[1,0]
	v_pk_mul_f32 v[90:91], v[88:89], v[96:97] op_sel_hi:[1,0]
	v_cvt_pk_bf16_f32 v88, v92, v93
	v_cvt_pk_bf16_f32 v89, v94, v95
	v_pk_mul_f32 v[86:87], v[86:87], v[96:97] op_sel_hi:[1,0]
	v_cvt_pk_bf16_f32 v90, v90, v91
	v_cvt_pk_bf16_f32 v91, v100, v101
	ds_bpermute_b32 v208, v230, v88
	ds_bpermute_b32 v209, v230, v89
	ds_bpermute_b32 v210, v230, v90
	ds_bpermute_b32 v211, v230, v91
	v_pk_mul_f32 v[84:85], v[84:85], v[96:97] op_sel_hi:[1,0]
	s_nop 0
	v_pk_mul_f32 v[88:89], v[82:83], v[96:97] op_sel_hi:[1,0]
	v_pk_mul_f32 v[82:83], v[80:81], v[96:97] op_sel_hi:[1,0]
	v_or_b32_e32 v96, 48, v154
	v_cvt_pk_bf16_f32 v80, v84, v85
	v_cvt_pk_bf16_f32 v81, v86, v87
	v_ashrrev_i32_e32 v97, 31, v96
	v_cvt_pk_bf16_f32 v82, v82, v83
	v_cvt_pk_bf16_f32 v83, v88, v89
	ds_bpermute_b32 v212, v230, v80
	ds_bpermute_b32 v213, v230, v81
	ds_bpermute_b32 v214, v230, v82
	ds_bpermute_b32 v215, v230, v83
	s_waitcnt lgkmcnt(4)
	global_store_dwordx4 v[98:99], v[208:211], off
	s_waitcnt lgkmcnt(0)
	global_store_dwordx4 v[98:99], v[212:215], off offset:256
	s_nop 1
	v_lshlrev_b64 v[80:81], 6, v[96:97]
	v_lshl_add_u64 v[92:93], s[90:91], 0, v[80:81]
	global_load_dwordx4 v[80:83], v[92:93], off offset:48
	global_load_dwordx4 v[84:87], v[92:93], off offset:32
	global_load_dwordx4 v[88:91], v[92:93], off offset:16
	s_nop 0
	global_load_dwordx4 v[92:95], v[92:93], off
	s_waitcnt vmcnt(2)
	v_add_f32_e32 v84, v84, v85
	v_add_f32_e32 v86, v86, v87
	s_waitcnt vmcnt(0)
	v_mov_b32_e32 v98, v93
	v_mov_b32_e32 v99, v94
	v_mov_b32_e32 v93, v95
	v_mov_b32_e32 v94, v89
	v_mov_b32_e32 v95, v90
	v_mov_b32_e32 v89, v91
	v_pk_add_f32 v[92:93], v[98:99], v[92:93]
	v_pk_add_f32 v[88:89], v[94:95], v[88:89]
	v_pk_add_f32 v[92:93], v[92:93], v[92:93] op_sel:[0,1] op_sel_hi:[1,0]
	v_pk_add_f32 v[88:89], v[88:89], v[88:89] op_sel:[0,1] op_sel_hi:[1,0]
	v_mov_b32_e32 v93, v80
	v_mov_b32_e32 v89, v81
	v_mov_b32_e32 v85, v82
	v_mov_b32_e32 v87, v83
	v_pk_add_f32 v[80:81], v[92:93], v[88:89]
	v_pk_add_f32 v[82:83], v[84:85], v[86:87]
	s_nop 0
	v_pk_add_f32 v[80:81], v[80:81], v[82:83]
	v_mad_i64_i32 v[82:83], s[24:25], v96, s49, 0
	v_add_f32_e32 v80, v80, v81
	v_fmamk_f32 v80, v80, 0x3a800000, v137
	v_cmp_gt_f32_e32 vcc, s4, v80
	v_mul_f32_e32 v81, 0x4b800000, v80
	v_lshl_add_u64 v[82:83], v[82:83], 1, s[78:79]
	v_cndmask_b32_e32 v80, v80, v81, vcc
	v_rsq_f32_e32 v80, v80
	v_lshl_add_u64 v[82:83], v[82:83], 0, v[152:153]
	v_mul_f32_e32 v81, 0x45800000, v80
	v_cndmask_b32_e32 v80, v80, v81, vcc
	v_pk_mul_f32 v[78:79], v[78:79], v[80:81] op_sel_hi:[1,0]
	v_pk_mul_f32 v[76:77], v[76:77], v[80:81] op_sel_hi:[1,0]
	v_pk_mul_f32 v[84:85], v[74:75], v[80:81] op_sel_hi:[1,0]
	v_pk_mul_f32 v[74:75], v[72:73], v[80:81] op_sel_hi:[1,0]
	v_cvt_pk_bf16_f32 v72, v76, v77
	v_cvt_pk_bf16_f32 v73, v78, v79
	v_pk_mul_f32 v[70:71], v[70:71], v[80:81] op_sel_hi:[1,0]
	v_cvt_pk_bf16_f32 v74, v74, v75
	v_cvt_pk_bf16_f32 v75, v84, v85
	ds_bpermute_b32 v208, v230, v72
	ds_bpermute_b32 v209, v230, v73
	ds_bpermute_b32 v210, v230, v74
	ds_bpermute_b32 v211, v230, v75
	v_pk_mul_f32 v[68:69], v[68:69], v[80:81] op_sel_hi:[1,0]
	s_nop 0
	v_pk_mul_f32 v[72:73], v[66:67], v[80:81] op_sel_hi:[1,0]
	v_pk_mul_f32 v[66:67], v[64:65], v[80:81] op_sel_hi:[1,0]
	v_add_u32_e32 v80, 0x80, v154
	v_cvt_pk_bf16_f32 v64, v68, v69
	v_cvt_pk_bf16_f32 v65, v70, v71
	v_ashrrev_i32_e32 v81, 31, v80
	v_cvt_pk_bf16_f32 v66, v66, v67
	v_cvt_pk_bf16_f32 v67, v72, v73
	ds_bpermute_b32 v212, v230, v64
	ds_bpermute_b32 v213, v230, v65
	ds_bpermute_b32 v214, v230, v66
	ds_bpermute_b32 v215, v230, v67
	s_waitcnt lgkmcnt(4)
	global_store_dwordx4 v[82:83], v[208:211], off
	s_waitcnt lgkmcnt(0)
; __device__ __forceinline__ unsigned cvt_pk_bf16(float lo, float hi) { unsigned r; asm volatile("v_cvt_pk_bf16_f32 %0, %1, %2" : "=v"(r) : "v"(lo), "v"(hi)); return r; }
;     __device__ __forceinline__ void operator()(const f32x4 (&acc)[2][2][4][2], const Unit& u, int wr, int wc, int fr, int fq) const {
;     ...
;                 const int row = row0 + ai * HALF + m * 16;
;                 const f32x4* sp = (const f32x4*)(ss + (size_t)row * 16);
;                 const f32x4 a0 = sp[0], a1 = sp[1], a2 = sp[2], a3 = sp[3];
;                 const float tot = ((a0.x + a0.y) + (a0.z + a0.w)) + ((a1.x + a1.y) + (a1.z + a1.w)) + ((a2.x + a2.y) + (a2.z + a2.w)) + ((a3.x + a3.y) + (a3.z + a3.w));
;                 const float rs = rsqrtf(tot * (1.0f / 1024.0f) + 1e-6f);
;                 bf16_t* rowp = O + (size_t)row * ldc + col0;
; #pragma unroll
;                 for (int bj = 0; bj < 2; ++bj) {
;                     f32x4 v0 = acc[ai][bj][m][0] * rs, v1 = acc[ai][bj][m][1] * rs;
;                     if (ACT == 1) {
; #pragma unroll
;                         for (int e = 0; e < 4; ++e) { float a = fmaxf(v0[e], 0.f); v0[e] = a * a; float b = fmaxf(v1[e], 0.f); v1[e] = b * b; }
;                     }
;                     u32x4 w; w.x = cvt_pk_bf16(v0[0], v0[1]); w.y = cvt_pk_bf16(v0[2], v0[3]); w.z = cvt_pk_bf16(v1[0], v1[1]); w.w = cvt_pk_bf16(v1[2], v1[3]);
;                     *(u32x4*)(rowp + bj * HALF) = w;
	global_store_dwordx4 v[82:83], v[212:215], off offset:256
	s_nop 1
	v_lshlrev_b64 v[64:65], 6, v[80:81]
	v_lshl_add_u64 v[76:77], s[90:91], 0, v[64:65]
	global_load_dwordx4 v[64:67], v[76:77], off offset:48
	global_load_dwordx4 v[68:71], v[76:77], off offset:32
	global_load_dwordx4 v[72:75], v[76:77], off offset:16
	s_nop 0
	global_load_dwordx4 v[76:79], v[76:77], off
	s_waitcnt vmcnt(2)
	v_add_f32_e32 v68, v68, v69
	v_add_f32_e32 v70, v70, v71
	s_waitcnt vmcnt(0)
	v_mov_b32_e32 v82, v77
	v_mov_b32_e32 v83, v78
	v_mov_b32_e32 v77, v79
	v_mov_b32_e32 v78, v73
	v_mov_b32_e32 v79, v74
	v_mov_b32_e32 v73, v75
	v_pk_add_f32 v[76:77], v[82:83], v[76:77]
	v_pk_add_f32 v[72:73], v[78:79], v[72:73]
	v_pk_add_f32 v[76:77], v[76:77], v[76:77] op_sel:[0,1] op_sel_hi:[1,0]
	v_pk_add_f32 v[72:73], v[72:73], v[72:73] op_sel:[0,1] op_sel_hi:[1,0]
	v_mov_b32_e32 v77, v64
	v_mov_b32_e32 v73, v65
	v_mov_b32_e32 v69, v66
	v_mov_b32_e32 v71, v67
	v_pk_add_f32 v[64:65], v[76:77], v[72:73]
	v_pk_add_f32 v[66:67], v[68:69], v[70:71]
	s_nop 0
	v_pk_add_f32 v[64:65], v[64:65], v[66:67]
	v_mad_i64_i32 v[66:67], s[24:25], v80, s49, 0
	v_add_f32_e32 v64, v64, v65
	v_fmamk_f32 v64, v64, 0x3a800000, v137
	v_cmp_gt_f32_e32 vcc, s4, v64
	v_mul_f32_e32 v65, 0x4b800000, v64
	v_lshl_add_u64 v[66:67], v[66:67], 1, s[78:79]
	v_cndmask_b32_e32 v64, v64, v65, vcc
	v_rsq_f32_e32 v64, v64
	v_lshl_add_u64 v[66:67], v[66:67], 0, v[152:153]
	v_mul_f32_e32 v65, 0x45800000, v64
	v_cndmask_b32_e32 v64, v64, v65, vcc
	v_pk_mul_f32 v[62:63], v[62:63], v[64:65] op_sel_hi:[1,0]
	v_pk_mul_f32 v[60:61], v[60:61], v[64:65] op_sel_hi:[1,0]
	v_pk_mul_f32 v[68:69], v[58:59], v[64:65] op_sel_hi:[1,0]
	v_pk_mul_f32 v[58:59], v[56:57], v[64:65] op_sel_hi:[1,0]
	v_cvt_pk_bf16_f32 v56, v60, v61
	v_cvt_pk_bf16_f32 v57, v62, v63
	v_pk_mul_f32 v[54:55], v[54:55], v[64:65] op_sel_hi:[1,0]
	v_cvt_pk_bf16_f32 v58, v58, v59
	v_cvt_pk_bf16_f32 v59, v68, v69
	ds_bpermute_b32 v208, v230, v56
	ds_bpermute_b32 v209, v230, v57
	ds_bpermute_b32 v210, v230, v58
	ds_bpermute_b32 v211, v230, v59
	v_pk_mul_f32 v[52:53], v[52:53], v[64:65] op_sel_hi:[1,0]
	s_nop 0
	v_pk_mul_f32 v[56:57], v[50:51], v[64:65] op_sel_hi:[1,0]
	v_pk_mul_f32 v[50:51], v[48:49], v[64:65] op_sel_hi:[1,0]
	v_add_u32_e32 v64, 0x90, v154
	v_cvt_pk_bf16_f32 v48, v52, v53
	v_cvt_pk_bf16_f32 v49, v54, v55
	v_ashrrev_i32_e32 v65, 31, v64
	v_cvt_pk_bf16_f32 v50, v50, v51
	v_cvt_pk_bf16_f32 v51, v56, v57
	ds_bpermute_b32 v212, v230, v48
	ds_bpermute_b32 v213, v230, v49
	ds_bpermute_b32 v214, v230, v50
	ds_bpermute_b32 v215, v230, v51
	s_waitcnt lgkmcnt(4)
	global_store_dwordx4 v[66:67], v[208:211], off
	s_waitcnt lgkmcnt(0)
	global_store_dwordx4 v[66:67], v[212:215], off offset:256
	s_nop 1
	v_lshlrev_b64 v[48:49], 6, v[64:65]
	v_lshl_add_u64 v[60:61], s[90:91], 0, v[48:49]
	global_load_dwordx4 v[48:51], v[60:61], off offset:48
	global_load_dwordx4 v[52:55], v[60:61], off offset:32
	global_load_dwordx4 v[56:59], v[60:61], off offset:16
	s_nop 0
	global_load_dwordx4 v[60:63], v[60:61], off
	s_waitcnt vmcnt(2)
	v_add_f32_e32 v52, v52, v53
	v_add_f32_e32 v54, v54, v55
	s_waitcnt vmcnt(0)
	v_mov_b32_e32 v66, v61
	v_mov_b32_e32 v67, v62
	v_mov_b32_e32 v61, v63
	v_mov_b32_e32 v62, v57
	v_mov_b32_e32 v63, v58
	v_mov_b32_e32 v57, v59
	v_pk_add_f32 v[60:61], v[66:67], v[60:61]
	v_pk_add_f32 v[56:57], v[62:63], v[56:57]
	v_pk_add_f32 v[60:61], v[60:61], v[60:61] op_sel:[0,1] op_sel_hi:[1,0]
	v_pk_add_f32 v[56:57], v[56:57], v[56:57] op_sel:[0,1] op_sel_hi:[1,0]
	v_mov_b32_e32 v61, v48
	v_mov_b32_e32 v57, v49
	v_mov_b32_e32 v53, v50
	v_mov_b32_e32 v55, v51
	v_pk_add_f32 v[48:49], v[60:61], v[56:57]
	v_pk_add_f32 v[50:51], v[52:53], v[54:55]
	s_nop 0
	v_pk_add_f32 v[48:49], v[48:49], v[50:51]
	v_mad_i64_i32 v[50:51], s[24:25], v64, s49, 0
	v_add_f32_e32 v48, v48, v49
	v_fmamk_f32 v48, v48, 0x3a800000, v137
	v_cmp_gt_f32_e32 vcc, s4, v48
	v_mul_f32_e32 v49, 0x4b800000, v48
	v_lshl_add_u64 v[50:51], v[50:51], 1, s[78:79]
	v_cndmask_b32_e32 v48, v48, v49, vcc
	v_rsq_f32_e32 v48, v48
	v_lshl_add_u64 v[50:51], v[50:51], 0, v[152:153]
	v_mul_f32_e32 v49, 0x45800000, v48
	v_cndmask_b32_e32 v48, v48, v49, vcc
	v_pk_mul_f32 v[46:47], v[46:47], v[48:49] op_sel_hi:[1,0]
	v_pk_mul_f32 v[44:45], v[44:45], v[48:49] op_sel_hi:[1,0]
	v_pk_mul_f32 v[52:53], v[42:43], v[48:49] op_sel_hi:[1,0]
	v_pk_mul_f32 v[42:43], v[40:41], v[48:49] op_sel_hi:[1,0]
	v_cvt_pk_bf16_f32 v40, v44, v45
	v_cvt_pk_bf16_f32 v41, v46, v47
	v_pk_mul_f32 v[38:39], v[38:39], v[48:49] op_sel_hi:[1,0]
	v_cvt_pk_bf16_f32 v42, v42, v43
	v_cvt_pk_bf16_f32 v43, v52, v53
	ds_bpermute_b32 v208, v230, v40
	ds_bpermute_b32 v209, v230, v41
	ds_bpermute_b32 v210, v230, v42
	ds_bpermute_b32 v211, v230, v43
	v_pk_mul_f32 v[36:37], v[36:37], v[48:49] op_sel_hi:[1,0]
	s_nop 0
	v_pk_mul_f32 v[40:41], v[34:35], v[48:49] op_sel_hi:[1,0]
	v_pk_mul_f32 v[34:35], v[32:33], v[48:49] op_sel_hi:[1,0]
	v_add_u32_e32 v48, 0xa0, v154
	v_cvt_pk_bf16_f32 v32, v36, v37
	v_cvt_pk_bf16_f32 v33, v38, v39
	v_ashrrev_i32_e32 v49, 31, v48
	v_cvt_pk_bf16_f32 v34, v34, v35
	v_cvt_pk_bf16_f32 v35, v40, v41
	ds_bpermute_b32 v212, v230, v32
	ds_bpermute_b32 v213, v230, v33
	ds_bpermute_b32 v214, v230, v34
	ds_bpermute_b32 v215, v230, v35
	s_waitcnt lgkmcnt(4)
	global_store_dwordx4 v[50:51], v[208:211], off
	s_waitcnt lgkmcnt(0)
; __device__ __forceinline__ unsigned cvt_pk_bf16(float lo, float hi) { unsigned r; asm volatile("v_cvt_pk_bf16_f32 %0, %1, %2" : "=v"(r) : "v"(lo), "v"(hi)); return r; }
; #define PG8_BAR __builtin_amdgcn_s_barrier()
;     __device__ __forceinline__ void operator()(const f32x4 (&acc)[2][2][4][2], const Unit& u, int wr, int wc, int fr, int fq) const {
;     ...
;                 const int row = row0 + ai * HALF + m * 16;
;                 const f32x4* sp = (const f32x4*)(ss + (size_t)row * 16);
;                 const f32x4 a0 = sp[0], a1 = sp[1], a2 = sp[2], a3 = sp[3];
;                 const float tot = ((a0.x + a0.y) + (a0.z + a0.w)) + ((a1.x + a1.y) + (a1.z + a1.w)) + ((a2.x + a2.y) + (a2.z + a2.w)) + ((a3.x + a3.y) + (a3.z + a3.w));
;                 const float rs = rsqrtf(tot * (1.0f / 1024.0f) + 1e-6f);
;                 bf16_t* rowp = O + (size_t)row * ldc + col0;
; #pragma unroll
;                 for (int bj = 0; bj < 2; ++bj) {
;                     f32x4 v0 = acc[ai][bj][m][0] * rs, v1 = acc[ai][bj][m][1] * rs;
;                     if (ACT == 1) {
; #pragma unroll
;                         for (int e = 0; e < 4; ++e) { float a = fmaxf(v0[e], 0.f); v0[e] = a * a; float b = fmaxf(v1[e], 0.f); v1[e] = b * b; }
;                     }
;                     u32x4 w; w.x = cvt_pk_bf16(v0[0], v0[1]); w.y = cvt_pk_bf16(v0[2], v0[3]); w.z = cvt_pk_bf16(v1[0], v1[1]); w.w = cvt_pk_bf16(v1[2], v1[3]);
;                     *(u32x4*)(rowp + bj * HALF) = w;
; template <class Epi, class Sched, bool ALIGN_EPI = false, bool SP2 = false>
; __device__ __forceinline__ void gemm_phase(PG8_LAS unsigned char* lds, const Gemm g, const Sched& S, const Epi& E) {
;     ...
;         if constexpr (ALIGN_EPI) { if (wr == 0) PG8_BAR; }
;         if constexpr (!Epi::AFTER_DRAIN) { E(acc, cur, wr, wc, fr, fq); S.done(cur); }
;         if (!has_next) break;
; #pragma unroll
;         for (int a = 0; a < 2; ++a)
; #pragma unroll
;             for (int b = 0; b < 2; ++b)
; #pragma unroll
;                 for (int m = 0; m < 4; ++m)
; #pragma unroll
;                     for (int n = 0; n < 2; ++n) acc[a][b][m][n] = (f32x4){0.f, 0.f, 0.f, 0.f};
;         cur = nxt; cA = nA; cB = nB; ++ui;
;         if constexpr (ALIGN_EPI) { if (wr == 1) PG8_BAR; }
	global_store_dwordx4 v[50:51], v[212:215], off offset:256
	s_nop 1
	v_lshlrev_b64 v[32:33], 6, v[48:49]
	v_lshl_add_u64 v[44:45], s[90:91], 0, v[32:33]
	global_load_dwordx4 v[32:35], v[44:45], off offset:48
	global_load_dwordx4 v[36:39], v[44:45], off offset:32
	global_load_dwordx4 v[40:43], v[44:45], off offset:16
	s_nop 0
	global_load_dwordx4 v[44:47], v[44:45], off
	s_waitcnt vmcnt(2)
	v_add_f32_e32 v36, v36, v37
	v_add_f32_e32 v38, v38, v39
	s_waitcnt vmcnt(0)
	v_mov_b32_e32 v50, v45
	v_mov_b32_e32 v51, v46
	v_mov_b32_e32 v45, v47
	v_mov_b32_e32 v46, v41
	v_mov_b32_e32 v47, v42
	v_mov_b32_e32 v41, v43
	v_pk_add_f32 v[44:45], v[50:51], v[44:45]
	v_pk_add_f32 v[40:41], v[46:47], v[40:41]
	v_pk_add_f32 v[44:45], v[44:45], v[44:45] op_sel:[0,1] op_sel_hi:[1,0]
	v_pk_add_f32 v[40:41], v[40:41], v[40:41] op_sel:[0,1] op_sel_hi:[1,0]
	v_mov_b32_e32 v45, v32
	v_mov_b32_e32 v41, v33
	v_mov_b32_e32 v37, v34
	v_mov_b32_e32 v39, v35
	v_pk_add_f32 v[32:33], v[44:45], v[40:41]
	v_pk_add_f32 v[34:35], v[36:37], v[38:39]
	s_nop 0
	v_pk_add_f32 v[32:33], v[32:33], v[34:35]
	v_mad_i64_i32 v[34:35], s[24:25], v48, s49, 0
	v_add_f32_e32 v32, v32, v33
	v_fmamk_f32 v32, v32, 0x3a800000, v137
	v_cmp_gt_f32_e32 vcc, s4, v32
	v_mul_f32_e32 v33, 0x4b800000, v32
	v_lshl_add_u64 v[34:35], v[34:35], 1, s[78:79]
	v_cndmask_b32_e32 v32, v32, v33, vcc
	v_rsq_f32_e32 v32, v32
	v_lshl_add_u64 v[34:35], v[34:35], 0, v[152:153]
	v_mul_f32_e32 v33, 0x45800000, v32
	v_cndmask_b32_e32 v32, v32, v33, vcc
	v_pk_mul_f32 v[30:31], v[30:31], v[32:33] op_sel_hi:[1,0]
	v_pk_mul_f32 v[28:29], v[28:29], v[32:33] op_sel_hi:[1,0]
	v_pk_mul_f32 v[36:37], v[26:27], v[32:33] op_sel_hi:[1,0]
	v_pk_mul_f32 v[26:27], v[24:25], v[32:33] op_sel_hi:[1,0]
	v_cvt_pk_bf16_f32 v24, v28, v29
	v_cvt_pk_bf16_f32 v25, v30, v31
	v_pk_mul_f32 v[22:23], v[22:23], v[32:33] op_sel_hi:[1,0]
	v_cvt_pk_bf16_f32 v26, v26, v27
	v_cvt_pk_bf16_f32 v27, v36, v37
	ds_bpermute_b32 v208, v230, v24
	ds_bpermute_b32 v209, v230, v25
	ds_bpermute_b32 v210, v230, v26
	ds_bpermute_b32 v211, v230, v27
	v_pk_mul_f32 v[20:21], v[20:21], v[32:33] op_sel_hi:[1,0]
	s_nop 0
	v_pk_mul_f32 v[24:25], v[18:19], v[32:33] op_sel_hi:[1,0]
	v_pk_mul_f32 v[18:19], v[16:17], v[32:33] op_sel_hi:[1,0]
	v_add_u32_e32 v32, 0xb0, v154
	v_cvt_pk_bf16_f32 v16, v20, v21
	v_cvt_pk_bf16_f32 v17, v22, v23
	v_ashrrev_i32_e32 v33, 31, v32
	v_cvt_pk_bf16_f32 v18, v18, v19
	v_cvt_pk_bf16_f32 v19, v24, v25
	ds_bpermute_b32 v212, v230, v16
	ds_bpermute_b32 v213, v230, v17
	ds_bpermute_b32 v214, v230, v18
	ds_bpermute_b32 v215, v230, v19
	s_waitcnt lgkmcnt(4)
	global_store_dwordx4 v[34:35], v[208:211], off
	s_waitcnt lgkmcnt(0)
	global_store_dwordx4 v[34:35], v[212:215], off offset:256
	s_nop 1
	v_lshlrev_b64 v[16:17], 6, v[32:33]
	v_lshl_add_u64 v[28:29], s[90:91], 0, v[16:17]
	global_load_dwordx4 v[16:19], v[28:29], off offset:48
	global_load_dwordx4 v[20:23], v[28:29], off offset:32
	global_load_dwordx4 v[24:27], v[28:29], off offset:16
	s_nop 0
	global_load_dwordx4 v[28:31], v[28:29], off
	s_waitcnt vmcnt(2)
	v_add_f32_e32 v20, v20, v21
	v_add_f32_e32 v22, v22, v23
	s_waitcnt vmcnt(0)
	v_mov_b32_e32 v34, v29
	v_mov_b32_e32 v35, v30
	v_mov_b32_e32 v29, v31
	v_mov_b32_e32 v30, v25
	v_mov_b32_e32 v31, v26
	v_mov_b32_e32 v25, v27
	v_pk_add_f32 v[28:29], v[34:35], v[28:29]
	v_pk_add_f32 v[24:25], v[30:31], v[24:25]
	v_pk_add_f32 v[28:29], v[28:29], v[28:29] op_sel:[0,1] op_sel_hi:[1,0]
	v_pk_add_f32 v[24:25], v[24:25], v[24:25] op_sel:[0,1] op_sel_hi:[1,0]
	v_mov_b32_e32 v29, v16
	v_mov_b32_e32 v25, v17
	v_mov_b32_e32 v21, v18
	v_mov_b32_e32 v23, v19
	v_pk_add_f32 v[16:17], v[28:29], v[24:25]
	v_pk_add_f32 v[18:19], v[20:21], v[22:23]
	s_nop 0
	v_pk_add_f32 v[16:17], v[16:17], v[18:19]
	v_mad_i64_i32 v[18:19], s[24:25], v32, s49, 0
	v_add_f32_e32 v16, v16, v17
	v_fmamk_f32 v16, v16, 0x3a800000, v137
	v_cmp_gt_f32_e32 vcc, s4, v16
	v_mul_f32_e32 v17, 0x4b800000, v16
	v_lshl_add_u64 v[18:19], v[18:19], 1, s[78:79]
	v_cndmask_b32_e32 v16, v16, v17, vcc
	v_rsq_f32_e32 v16, v16
	v_lshl_add_u64 v[18:19], v[18:19], 0, v[152:153]
	s_mov_b64 s[24:25], -1
	v_mul_f32_e32 v17, 0x45800000, v16
	v_cndmask_b32_e32 v16, v16, v17, vcc
	v_pk_mul_f32 v[14:15], v[14:15], v[16:17] op_sel_hi:[1,0]
	v_pk_mul_f32 v[12:13], v[12:13], v[16:17] op_sel_hi:[1,0]
	v_pk_mul_f32 v[20:21], v[10:11], v[16:17] op_sel_hi:[1,0]
	v_pk_mul_f32 v[10:11], v[8:9], v[16:17] op_sel_hi:[1,0]
	v_cvt_pk_bf16_f32 v8, v12, v13
	v_cvt_pk_bf16_f32 v9, v14, v15
	s_andn2_b64 vcc, exec, s[36:37]
	v_cvt_pk_bf16_f32 v10, v10, v11
	v_cvt_pk_bf16_f32 v11, v20, v21
	ds_bpermute_b32 v208, v230, v8
	ds_bpermute_b32 v209, v230, v9
	ds_bpermute_b32 v210, v230, v10
	ds_bpermute_b32 v211, v230, v11
	v_pk_mul_f32 v[6:7], v[6:7], v[16:17] op_sel_hi:[1,0]
	v_pk_mul_f32 v[4:5], v[4:5], v[16:17] op_sel_hi:[1,0]
	v_pk_mul_f32 v[8:9], v[2:3], v[16:17] op_sel_hi:[1,0]
	v_pk_mul_f32 v[2:3], v[0:1], v[16:17] op_sel_hi:[1,0]
	v_cvt_pk_bf16_f32 v0, v4, v5
	v_cvt_pk_bf16_f32 v1, v6, v7
	s_nop 0
	v_cvt_pk_bf16_f32 v2, v2, v3
	v_cvt_pk_bf16_f32 v3, v8, v9
	ds_bpermute_b32 v212, v230, v0
	ds_bpermute_b32 v213, v230, v1
	ds_bpermute_b32 v214, v230, v2
	ds_bpermute_b32 v215, v230, v3
	s_waitcnt lgkmcnt(4)
	global_store_dwordx4 v[18:19], v[208:211], off
	s_waitcnt lgkmcnt(0)
	global_store_dwordx4 v[18:19], v[212:215], off offset:256
	s_cbranch_vccnz .LBB0_422
	v_readlane_b32 s24, v250, 34
	v_readlane_b32 s25, v250, 35
	s_andn2_b64 vcc, exec, s[24:25]
	s_cbranch_vccnz .LBB0_421
	s_barrier
	s_branch .LBB0_421
